# sc1 write-through on dwordx4 epilogue stores of out-GEMM/AO/BO/QKV/BQ phases (cheaper L2 writeback at grid barrier)
# baseline (speedup 1.0000x reference)
.LBB0_267:
	v_lshl_add_u32 v152, s82, 8, v146
	v_lshl_or_b32 v144, s83, 8, v148
	v_ashrrev_i32_e32 v145, 31, v144
	v_ashrrev_i32_e32 v153, 31, v152
	v_lshl_add_u64 v[154:155], v[144:145], 1, s[24:25]
	v_lshlrev_b64 v[144:145], 11, v[152:153]
	v_lshl_add_u64 v[144:145], v[154:155], 0, v[144:145]
	s_nop 15
	s_nop 7
	v_cvt_pk_bf16_f32 v124, v124, v125
	v_cvt_pk_bf16_f32 v125, v126, v127
	v_cvt_pk_bf16_f32 v126, v120, v121
	v_cvt_pk_bf16_f32 v127, v122, v123
	global_store_dwordx4 v[144:145], v[124:127], off sc1
	v_cvt_pk_bf16_f32 v112, v112, v113
	v_cvt_pk_bf16_f32 v113, v114, v115
	v_cvt_pk_bf16_f32 v114, v104, v105
	v_or_b32_e32 v104, 16, v152
	v_ashrrev_i32_e32 v105, 31, v104
	v_lshlrev_b64 v[104:105], 11, v[104:105]
	v_cvt_pk_bf16_f32 v115, v106, v107
	global_store_dwordx4 v[144:145], v[112:115], off offset:256 sc1
	s_nop 1
	v_lshl_add_u64 v[112:113], v[154:155], 0, v[104:105]
	v_cvt_pk_bf16_f32 v104, v116, v117
	v_cvt_pk_bf16_f32 v105, v118, v119
	v_cvt_pk_bf16_f32 v106, v108, v109
	v_cvt_pk_bf16_f32 v107, v110, v111
	global_store_dwordx4 v[112:113], v[104:107], off sc1
	v_cvt_pk_bf16_f32 v96, v96, v97
	v_cvt_pk_bf16_f32 v97, v98, v99
	v_cvt_pk_bf16_f32 v98, v88, v89
	v_or_b32_e32 v88, 32, v152
	v_ashrrev_i32_e32 v89, 31, v88
	v_lshlrev_b64 v[88:89], 11, v[88:89]
	v_cvt_pk_bf16_f32 v99, v90, v91
	global_store_dwordx4 v[112:113], v[96:99], off offset:256 sc1
	s_nop 1
	v_lshl_add_u64 v[96:97], v[154:155], 0, v[88:89]
	v_cvt_pk_bf16_f32 v88, v100, v101
	v_cvt_pk_bf16_f32 v89, v102, v103
	v_cvt_pk_bf16_f32 v90, v92, v93
	v_cvt_pk_bf16_f32 v91, v94, v95
	global_store_dwordx4 v[96:97], v[88:91], off sc1
	v_cvt_pk_bf16_f32 v80, v80, v81
	v_cvt_pk_bf16_f32 v81, v82, v83
	v_cvt_pk_bf16_f32 v82, v72, v73
	v_or_b32_e32 v72, 48, v152
	v_ashrrev_i32_e32 v73, 31, v72
	v_lshlrev_b64 v[72:73], 11, v[72:73]
	v_cvt_pk_bf16_f32 v83, v74, v75
	global_store_dwordx4 v[96:97], v[80:83], off offset:256 sc1
	s_nop 1
	v_lshl_add_u64 v[80:81], v[154:155], 0, v[72:73]
	v_cvt_pk_bf16_f32 v72, v84, v85
	v_cvt_pk_bf16_f32 v73, v86, v87
	v_cvt_pk_bf16_f32 v74, v76, v77
	v_cvt_pk_bf16_f32 v75, v78, v79
	global_store_dwordx4 v[80:81], v[72:75], off sc1
	v_cvt_pk_bf16_f32 v68, v68, v69
	v_cvt_pk_bf16_f32 v69, v70, v71
	v_cvt_pk_bf16_f32 v70, v64, v65
	v_cvt_pk_bf16_f32 v71, v66, v67
	global_store_dwordx4 v[80:81], v[68:71], off offset:256 sc1
	v_cvt_pk_bf16_f32 v60, v60, v61
	v_cvt_pk_bf16_f32 v61, v62, v63
	v_cvt_pk_bf16_f32 v62, v56, v57
	v_add_co_u32_e32 v56, vcc, s72, v144
	v_lshl_add_u64 v[64:65], v[144:145], 0, s[30:31]
	s_nop 0
	v_addc_co_u32_e32 v57, vcc, 0, v145, vcc
	v_cvt_pk_bf16_f32 v63, v58, v59
	global_store_dwordx4 v[56:57], v[60:63], off sc1
	v_cvt_pk_bf16_f32 v48, v48, v49
	v_cvt_pk_bf16_f32 v49, v50, v51
	v_cvt_pk_bf16_f32 v50, v40, v41
	v_cvt_pk_bf16_f32 v51, v42, v43
	global_store_dwordx4 v[64:65], v[48:51], off offset:256 sc1
	v_cvt_pk_bf16_f32 v40, v52, v53
	v_cvt_pk_bf16_f32 v41, v54, v55
	v_cvt_pk_bf16_f32 v42, v44, v45
	v_add_co_u32_e32 v44, vcc, s73, v144
	s_nop 0
	v_lshl_add_u64 v[48:49], v[144:145], 0, s[36:37]
	v_addc_co_u32_e32 v45, vcc, 0, v145, vcc
	v_cvt_pk_bf16_f32 v43, v46, v47
	global_store_dwordx4 v[44:45], v[40:43], off sc1
	v_cvt_pk_bf16_f32 v32, v32, v33
	v_cvt_pk_bf16_f32 v33, v34, v35
	v_cvt_pk_bf16_f32 v34, v24, v25
	v_cvt_pk_bf16_f32 v35, v26, v27
	global_store_dwordx4 v[48:49], v[32:35], off offset:256 sc1
	v_cvt_pk_bf16_f32 v24, v36, v37
	v_cvt_pk_bf16_f32 v25, v38, v39
	v_cvt_pk_bf16_f32 v26, v28, v29
	v_add_co_u32_e32 v28, vcc, s74, v144
	s_nop 0
	v_lshl_add_u64 v[32:33], v[144:145], 0, s[44:45]
	v_addc_co_u32_e32 v29, vcc, 0, v145, vcc
	v_cvt_pk_bf16_f32 v27, v30, v31
	global_store_dwordx4 v[28:29], v[24:27], off sc1
	v_cvt_pk_bf16_f32 v16, v16, v17
	v_cvt_pk_bf16_f32 v17, v18, v19
	v_cvt_pk_bf16_f32 v18, v8, v9
	v_cvt_pk_bf16_f32 v19, v10, v11
	global_store_dwordx4 v[32:33], v[16:19], off offset:256 sc1
	v_cvt_pk_bf16_f32 v8, v20, v21
	v_cvt_pk_bf16_f32 v9, v22, v23
	v_cvt_pk_bf16_f32 v10, v12, v13
	v_add_co_u32_e32 v12, vcc, s75, v144
	s_nop 0
	v_lshl_add_u64 v[16:17], v[144:145], 0, s[46:47]
	v_addc_co_u32_e32 v13, vcc, 0, v145, vcc
	s_and_b64 vcc, exec, s[4:5]
	s_mov_b64 s[4:5], -1
	v_cvt_pk_bf16_f32 v11, v14, v15
	global_store_dwordx4 v[12:13], v[8:11], off sc1
	v_cvt_pk_bf16_f32 v4, v4, v5
	v_cvt_pk_bf16_f32 v5, v6, v7
	v_cvt_pk_bf16_f32 v6, v0, v1
	v_cvt_pk_bf16_f32 v7, v2, v3
	global_store_dwordx4 v[16:17], v[4:7], off offset:256 sc1
	s_cbranch_vccnz .LBB0_252
	s_andn2_b64 vcc, exec, s[0:1]
	s_cbranch_vccnz .LBB0_251
	s_barrier
	s_branch .LBB0_251

.LBB0_390:
	s_lshl_b32 s18, s57, 8
	s_or_b32 s18, s18, s73
	v_lshl_add_u32 v152, s56, 8, v146
	s_ashr_i32 s56, s18, 6
	s_ashr_i32 s57, s56, 31
	s_lshl_b64 s[58:59], s[56:57], 22
	s_cmp_lt_i32 s56, 16
	s_cselect_b64 vcc, -1, 0
	v_cndmask_b32_e32 v156, 1.0, v151, vcc
	v_pk_mul_f32 v[124:125], v[156:157], v[124:125] op_sel_hi:[0,1]
	v_ashrrev_i32_e32 v153, 31, v152
	v_lshl_add_u64 v[154:155], v[136:137], 0, s[58:59]
	v_pk_mul_f32 v[126:127], v[156:157], v[126:127] op_sel_hi:[0,1]
	v_pk_mul_f32 v[158:159], v[156:157], v[122:123] op_sel_hi:[0,1]
	v_pk_mul_f32 v[122:123], v[156:157], v[120:121] op_sel_hi:[0,1]
	v_cvt_pk_bf16_f32 v120, v124, v125
	v_lshlrev_b64 v[124:125], 7, v[152:153]
	v_cvt_pk_bf16_f32 v121, v126, v127
	v_lshl_add_u64 v[126:127], v[154:155], 0, v[124:125]
	v_pk_mul_f32 v[116:117], v[156:157], v[116:117] op_sel_hi:[0,1]
	v_cvt_pk_bf16_f32 v122, v122, v123
	v_cvt_pk_bf16_f32 v123, v158, v159
	global_store_dwordx4 v[126:127], v[120:123], off sc1
	v_pk_mul_f32 v[118:119], v[156:157], v[118:119] op_sel_hi:[0,1]
	v_pk_mul_f32 v[108:109], v[156:157], v[108:109] op_sel_hi:[0,1]
	v_pk_mul_f32 v[120:121], v[156:157], v[114:115] op_sel_hi:[0,1]
	v_pk_mul_f32 v[114:115], v[156:157], v[112:113] op_sel_hi:[0,1]
	v_cvt_pk_bf16_f32 v112, v116, v117
	v_or_b32_e32 v116, 16, v152
	v_ashrrev_i32_e32 v117, 31, v116
	v_lshlrev_b64 v[116:117], 7, v[116:117]
	v_cvt_pk_bf16_f32 v113, v118, v119
	v_lshl_add_u64 v[118:119], v[154:155], 0, v[116:117]
	v_cvt_pk_bf16_f32 v114, v114, v115
	v_cvt_pk_bf16_f32 v115, v120, v121
	global_store_dwordx4 v[118:119], v[112:115], off sc1
	v_pk_mul_f32 v[110:111], v[156:157], v[110:111] op_sel_hi:[0,1]
	v_pk_mul_f32 v[100:101], v[156:157], v[100:101] op_sel_hi:[0,1]
	v_pk_mul_f32 v[112:113], v[156:157], v[106:107] op_sel_hi:[0,1]
	v_pk_mul_f32 v[106:107], v[156:157], v[104:105] op_sel_hi:[0,1]
	v_cvt_pk_bf16_f32 v104, v108, v109
	v_or_b32_e32 v108, 32, v152
	v_ashrrev_i32_e32 v109, 31, v108
	v_lshlrev_b64 v[108:109], 7, v[108:109]
	v_cvt_pk_bf16_f32 v105, v110, v111
	v_lshl_add_u64 v[110:111], v[154:155], 0, v[108:109]
	v_cvt_pk_bf16_f32 v106, v106, v107
	v_cvt_pk_bf16_f32 v107, v112, v113
	global_store_dwordx4 v[110:111], v[104:107], off sc1
	v_pk_mul_f32 v[102:103], v[156:157], v[102:103] op_sel_hi:[0,1]
	v_pk_mul_f32 v[92:93], v[156:157], v[92:93] op_sel_hi:[0,1]
	v_pk_mul_f32 v[104:105], v[156:157], v[98:99] op_sel_hi:[0,1]
	v_pk_mul_f32 v[98:99], v[156:157], v[96:97] op_sel_hi:[0,1]
	v_cvt_pk_bf16_f32 v96, v100, v101
	v_or_b32_e32 v100, 48, v152
	v_ashrrev_i32_e32 v101, 31, v100
	v_lshlrev_b64 v[100:101], 7, v[100:101]
	v_cvt_pk_bf16_f32 v97, v102, v103
	v_lshl_add_u64 v[102:103], v[154:155], 0, v[100:101]
	v_cvt_pk_bf16_f32 v98, v98, v99
	v_cvt_pk_bf16_f32 v99, v104, v105
	global_store_dwordx4 v[102:103], v[96:99], off sc1
	v_pk_mul_f32 v[94:95], v[156:157], v[94:95] op_sel_hi:[0,1]
	v_pk_mul_f32 v[84:85], v[156:157], v[84:85] op_sel_hi:[0,1]
	v_pk_mul_f32 v[96:97], v[156:157], v[90:91] op_sel_hi:[0,1]
	v_pk_mul_f32 v[90:91], v[156:157], v[88:89] op_sel_hi:[0,1]
	v_cvt_pk_bf16_f32 v88, v92, v93
	v_lshl_add_u64 v[92:93], v[124:125], 0, s[10:11]
	v_cvt_pk_bf16_f32 v89, v94, v95
	v_lshl_add_u64 v[94:95], v[154:155], 0, v[92:93]
	v_cvt_pk_bf16_f32 v90, v90, v91
	v_cvt_pk_bf16_f32 v91, v96, v97
	global_store_dwordx4 v[94:95], v[88:91], off sc1
	v_pk_mul_f32 v[86:87], v[156:157], v[86:87] op_sel_hi:[0,1]
	s_or_b32 s56, s56, 2
	v_pk_mul_f32 v[88:89], v[156:157], v[82:83] op_sel_hi:[0,1]
	v_pk_mul_f32 v[82:83], v[156:157], v[80:81] op_sel_hi:[0,1]
	v_cvt_pk_bf16_f32 v80, v84, v85
	v_lshl_add_u64 v[84:85], v[124:125], 0, s[16:17]
	v_cvt_pk_bf16_f32 v81, v86, v87
	v_lshl_add_u64 v[86:87], v[154:155], 0, v[84:85]
	v_pk_mul_f32 v[76:77], v[156:157], v[76:77] op_sel_hi:[0,1]
	s_ashr_i32 s57, s56, 31
	v_cvt_pk_bf16_f32 v82, v82, v83
	v_cvt_pk_bf16_f32 v83, v88, v89
	global_store_dwordx4 v[86:87], v[80:83], off sc1
	v_pk_mul_f32 v[78:79], v[156:157], v[78:79] op_sel_hi:[0,1]
	s_lshl_b64 s[58:59], s[56:57], 22
	v_pk_mul_f32 v[80:81], v[156:157], v[74:75] op_sel_hi:[0,1]
	v_pk_mul_f32 v[74:75], v[156:157], v[72:73] op_sel_hi:[0,1]
	v_cvt_pk_bf16_f32 v72, v76, v77
	v_lshl_add_u64 v[76:77], v[124:125], 0, s[36:37]
	v_cvt_pk_bf16_f32 v73, v78, v79
	v_lshl_add_u64 v[78:79], v[154:155], 0, v[76:77]
	v_pk_mul_f32 v[60:61], v[156:157], v[60:61] op_sel_hi:[0,1]
	s_cmp_lt_i32 s56, 16
	v_cvt_pk_bf16_f32 v74, v74, v75
	v_cvt_pk_bf16_f32 v75, v80, v81
	global_store_dwordx4 v[78:79], v[72:75], off sc1
	v_pk_mul_f32 v[62:63], v[156:157], v[62:63] op_sel_hi:[0,1]
	s_cselect_b64 vcc, -1, 0
	v_pk_mul_f32 v[72:73], v[156:157], v[58:59] op_sel_hi:[0,1]
	v_pk_mul_f32 v[58:59], v[156:157], v[56:57] op_sel_hi:[0,1]
	v_cvt_pk_bf16_f32 v56, v60, v61
	v_lshl_add_u64 v[60:61], v[124:125], 0, s[44:45]
	v_cvt_pk_bf16_f32 v57, v62, v63
	v_cvt_pk_bf16_f32 v58, v58, v59
	v_cvt_pk_bf16_f32 v59, v72, v73
	v_lshl_add_u64 v[62:63], v[154:155], 0, v[60:61]
	v_cndmask_b32_e32 v72, 1.0, v151, vcc
	global_store_dwordx4 v[62:63], v[56:59], off sc1
	v_lshl_add_u64 v[62:63], v[136:137], 0, s[58:59]
	v_pk_mul_f32 v[64:65], v[72:73], v[64:65] op_sel_hi:[0,1]
	v_pk_mul_f32 v[58:59], v[72:73], v[70:71] op_sel_hi:[0,1]
	v_pk_mul_f32 v[56:57], v[72:73], v[68:69] op_sel_hi:[0,1]
	v_cvt_pk_bf16_f32 v56, v56, v57
	v_cvt_pk_bf16_f32 v57, v58, v59
	v_cvt_pk_bf16_f32 v58, v64, v65
	v_lshl_add_u64 v[64:65], v[62:63], 0, v[124:125]
	v_pk_mul_f32 v[52:53], v[72:73], v[52:53] op_sel_hi:[0,1]
	v_pk_mul_f32 v[66:67], v[72:73], v[66:67] op_sel_hi:[0,1]
	v_cvt_pk_bf16_f32 v59, v66, v67
	global_store_dwordx4 v[64:65], v[56:59], off sc1
	v_pk_mul_f32 v[54:55], v[72:73], v[54:55] op_sel_hi:[0,1]
	v_pk_mul_f32 v[44:45], v[72:73], v[44:45] op_sel_hi:[0,1]
	v_pk_mul_f32 v[56:57], v[72:73], v[50:51] op_sel_hi:[0,1]
	v_pk_mul_f32 v[50:51], v[72:73], v[48:49] op_sel_hi:[0,1]
	v_cvt_pk_bf16_f32 v48, v52, v53
	v_cvt_pk_bf16_f32 v49, v54, v55
	v_lshl_add_u64 v[52:53], v[62:63], 0, v[116:117]
	v_cvt_pk_bf16_f32 v50, v50, v51
	v_cvt_pk_bf16_f32 v51, v56, v57
	global_store_dwordx4 v[52:53], v[48:51], off sc1
	v_pk_mul_f32 v[46:47], v[72:73], v[46:47] op_sel_hi:[0,1]
	v_pk_mul_f32 v[36:37], v[72:73], v[36:37] op_sel_hi:[0,1]
	v_pk_mul_f32 v[48:49], v[72:73], v[42:43] op_sel_hi:[0,1]
	v_pk_mul_f32 v[42:43], v[72:73], v[40:41] op_sel_hi:[0,1]
	v_cvt_pk_bf16_f32 v40, v44, v45
	v_cvt_pk_bf16_f32 v41, v46, v47
	v_lshl_add_u64 v[44:45], v[62:63], 0, v[108:109]
	v_cvt_pk_bf16_f32 v42, v42, v43
	v_cvt_pk_bf16_f32 v43, v48, v49
	global_store_dwordx4 v[44:45], v[40:43], off sc1
	v_pk_mul_f32 v[38:39], v[72:73], v[38:39] op_sel_hi:[0,1]
	v_pk_mul_f32 v[28:29], v[72:73], v[28:29] op_sel_hi:[0,1]
	v_pk_mul_f32 v[40:41], v[72:73], v[34:35] op_sel_hi:[0,1]
	v_pk_mul_f32 v[34:35], v[72:73], v[32:33] op_sel_hi:[0,1]
	v_cvt_pk_bf16_f32 v32, v36, v37
	v_cvt_pk_bf16_f32 v33, v38, v39
	v_lshl_add_u64 v[36:37], v[62:63], 0, v[100:101]
	v_cvt_pk_bf16_f32 v34, v34, v35
	v_cvt_pk_bf16_f32 v35, v40, v41
	global_store_dwordx4 v[36:37], v[32:35], off sc1
	v_pk_mul_f32 v[30:31], v[72:73], v[30:31] op_sel_hi:[0,1]
	v_pk_mul_f32 v[20:21], v[72:73], v[20:21] op_sel_hi:[0,1]
	v_pk_mul_f32 v[32:33], v[72:73], v[26:27] op_sel_hi:[0,1]
	v_pk_mul_f32 v[26:27], v[72:73], v[24:25] op_sel_hi:[0,1]
	v_cvt_pk_bf16_f32 v24, v28, v29
	v_cvt_pk_bf16_f32 v25, v30, v31
	v_lshl_add_u64 v[28:29], v[62:63], 0, v[92:93]
	v_cvt_pk_bf16_f32 v26, v26, v27
	v_cvt_pk_bf16_f32 v27, v32, v33
	global_store_dwordx4 v[28:29], v[24:27], off sc1
	v_pk_mul_f32 v[22:23], v[72:73], v[22:23] op_sel_hi:[0,1]
	v_pk_mul_f32 v[12:13], v[72:73], v[12:13] op_sel_hi:[0,1]
	v_pk_mul_f32 v[24:25], v[72:73], v[18:19] op_sel_hi:[0,1]
	v_pk_mul_f32 v[18:19], v[72:73], v[16:17] op_sel_hi:[0,1]
	v_cvt_pk_bf16_f32 v16, v20, v21
	v_cvt_pk_bf16_f32 v17, v22, v23
	v_lshl_add_u64 v[20:21], v[62:63], 0, v[84:85]
	v_cvt_pk_bf16_f32 v18, v18, v19
	v_cvt_pk_bf16_f32 v19, v24, v25
	global_store_dwordx4 v[20:21], v[16:19], off sc1
	v_pk_mul_f32 v[14:15], v[72:73], v[14:15] op_sel_hi:[0,1]
	v_pk_mul_f32 v[4:5], v[72:73], v[4:5] op_sel_hi:[0,1]
	v_pk_mul_f32 v[16:17], v[72:73], v[10:11] op_sel_hi:[0,1]
	v_pk_mul_f32 v[10:11], v[72:73], v[8:9] op_sel_hi:[0,1]
	v_cvt_pk_bf16_f32 v8, v12, v13
	v_cvt_pk_bf16_f32 v9, v14, v15
	v_lshl_add_u64 v[12:13], v[62:63], 0, v[76:77]
	v_cvt_pk_bf16_f32 v10, v10, v11
	v_cvt_pk_bf16_f32 v11, v16, v17
	global_store_dwordx4 v[12:13], v[8:11], off sc1
	s_andn2_b64 vcc, exec, s[4:5]
	s_mov_b64 s[4:5], -1
	v_pk_mul_f32 v[8:9], v[72:73], v[2:3] op_sel_hi:[0,1]
	v_pk_mul_f32 v[2:3], v[72:73], v[0:1] op_sel_hi:[0,1]
	v_cvt_pk_bf16_f32 v0, v4, v5
	v_lshl_add_u64 v[4:5], v[62:63], 0, v[60:61]
	v_pk_mul_f32 v[6:7], v[72:73], v[6:7] op_sel_hi:[0,1]
	v_cvt_pk_bf16_f32 v1, v6, v7
	v_cvt_pk_bf16_f32 v2, v2, v3
	v_cvt_pk_bf16_f32 v3, v8, v9
	global_store_dwordx4 v[4:5], v[0:3], off sc1
	s_cbranch_vccnz .LBB0_383
	s_andn2_b64 vcc, exec, s[0:1]
	s_cbranch_vccnz .LBB0_382
	s_barrier
	s_branch .LBB0_382

.LBB0_604:
	v_lshl_add_u32 v152, s56, 8, v146
	v_lshl_or_b32 v144, s83, 8, v148
	v_ashrrev_i32_e32 v145, 31, v144
	v_ashrrev_i32_e32 v153, 31, v152
	v_lshl_add_u64 v[154:155], v[144:145], 1, s[24:25]
	v_lshlrev_b64 v[144:145], 11, v[152:153]
	v_lshl_add_u64 v[144:145], v[154:155], 0, v[144:145]
	s_nop 15
	s_nop 7
	v_cvt_pk_bf16_f32 v124, v124, v125
	v_cvt_pk_bf16_f32 v125, v126, v127
	v_cvt_pk_bf16_f32 v126, v120, v121
	v_cvt_pk_bf16_f32 v127, v122, v123
	global_store_dwordx4 v[144:145], v[124:127], off sc1
	v_cvt_pk_bf16_f32 v112, v112, v113
	v_cvt_pk_bf16_f32 v113, v114, v115
	v_cvt_pk_bf16_f32 v114, v104, v105
	v_or_b32_e32 v104, 16, v152
	v_ashrrev_i32_e32 v105, 31, v104
	v_lshlrev_b64 v[104:105], 11, v[104:105]
	v_cvt_pk_bf16_f32 v115, v106, v107
	global_store_dwordx4 v[144:145], v[112:115], off offset:256 sc1
	s_nop 1
	v_lshl_add_u64 v[112:113], v[154:155], 0, v[104:105]
	v_cvt_pk_bf16_f32 v104, v116, v117
	v_cvt_pk_bf16_f32 v105, v118, v119
	v_cvt_pk_bf16_f32 v106, v108, v109
	v_cvt_pk_bf16_f32 v107, v110, v111
	global_store_dwordx4 v[112:113], v[104:107], off sc1
	v_cvt_pk_bf16_f32 v96, v96, v97
	v_cvt_pk_bf16_f32 v97, v98, v99
	v_cvt_pk_bf16_f32 v98, v88, v89
	v_or_b32_e32 v88, 32, v152
	v_ashrrev_i32_e32 v89, 31, v88
	v_lshlrev_b64 v[88:89], 11, v[88:89]
	v_cvt_pk_bf16_f32 v99, v90, v91
	global_store_dwordx4 v[112:113], v[96:99], off offset:256 sc1
	s_nop 1
	v_lshl_add_u64 v[96:97], v[154:155], 0, v[88:89]
	v_cvt_pk_bf16_f32 v88, v100, v101
	v_cvt_pk_bf16_f32 v89, v102, v103
	v_cvt_pk_bf16_f32 v90, v92, v93
	v_cvt_pk_bf16_f32 v91, v94, v95
	global_store_dwordx4 v[96:97], v[88:91], off sc1
	v_cvt_pk_bf16_f32 v80, v80, v81
	v_cvt_pk_bf16_f32 v81, v82, v83
	v_cvt_pk_bf16_f32 v82, v72, v73
	v_or_b32_e32 v72, 48, v152
	v_ashrrev_i32_e32 v73, 31, v72
	v_lshlrev_b64 v[72:73], 11, v[72:73]
	v_cvt_pk_bf16_f32 v83, v74, v75
	global_store_dwordx4 v[96:97], v[80:83], off offset:256 sc1
	s_nop 1
	v_lshl_add_u64 v[80:81], v[154:155], 0, v[72:73]
	v_cvt_pk_bf16_f32 v72, v84, v85
	v_cvt_pk_bf16_f32 v73, v86, v87
	v_cvt_pk_bf16_f32 v74, v76, v77
	v_cvt_pk_bf16_f32 v75, v78, v79
	global_store_dwordx4 v[80:81], v[72:75], off sc1
	v_cvt_pk_bf16_f32 v68, v68, v69
	v_cvt_pk_bf16_f32 v69, v70, v71
	v_cvt_pk_bf16_f32 v70, v64, v65
	v_cvt_pk_bf16_f32 v71, v66, v67
	global_store_dwordx4 v[80:81], v[68:71], off offset:256 sc1
	v_cvt_pk_bf16_f32 v60, v60, v61
	v_cvt_pk_bf16_f32 v61, v62, v63
	v_cvt_pk_bf16_f32 v62, v56, v57
	v_add_co_u32_e32 v56, vcc, s75, v144
	v_lshl_add_u64 v[64:65], v[144:145], 0, s[0:1]
	s_nop 0
	v_addc_co_u32_e32 v57, vcc, 0, v145, vcc
	v_cvt_pk_bf16_f32 v63, v58, v59
	global_store_dwordx4 v[56:57], v[60:63], off sc1
	v_cvt_pk_bf16_f32 v48, v48, v49
	v_cvt_pk_bf16_f32 v49, v50, v51
	v_cvt_pk_bf16_f32 v50, v40, v41
	v_cvt_pk_bf16_f32 v51, v42, v43
	global_store_dwordx4 v[64:65], v[48:51], off offset:256 sc1
	v_cvt_pk_bf16_f32 v40, v52, v53
	v_cvt_pk_bf16_f32 v41, v54, v55
	v_cvt_pk_bf16_f32 v42, v44, v45
	v_add_co_u32_e32 v44, vcc, s76, v144
	s_nop 0
	v_lshl_add_u64 v[48:49], v[144:145], 0, s[16:17]
	v_addc_co_u32_e32 v45, vcc, 0, v145, vcc
	v_cvt_pk_bf16_f32 v43, v46, v47
	global_store_dwordx4 v[44:45], v[40:43], off sc1
	v_cvt_pk_bf16_f32 v32, v32, v33
	v_cvt_pk_bf16_f32 v33, v34, v35
	v_cvt_pk_bf16_f32 v34, v24, v25
	v_cvt_pk_bf16_f32 v35, v26, v27
	global_store_dwordx4 v[48:49], v[32:35], off offset:256 sc1
	v_cvt_pk_bf16_f32 v24, v36, v37
	v_cvt_pk_bf16_f32 v25, v38, v39
	v_cvt_pk_bf16_f32 v26, v28, v29
	v_add_co_u32_e32 v28, vcc, s77, v144
	s_nop 0
	v_lshl_add_u64 v[32:33], v[144:145], 0, s[36:37]
	v_addc_co_u32_e32 v29, vcc, 0, v145, vcc
	v_cvt_pk_bf16_f32 v27, v30, v31
	global_store_dwordx4 v[28:29], v[24:27], off sc1
	v_cvt_pk_bf16_f32 v16, v16, v17
	v_cvt_pk_bf16_f32 v17, v18, v19
	v_cvt_pk_bf16_f32 v18, v8, v9
	v_cvt_pk_bf16_f32 v19, v10, v11
	global_store_dwordx4 v[32:33], v[16:19], off offset:256 sc1
	v_cvt_pk_bf16_f32 v8, v20, v21
	v_cvt_pk_bf16_f32 v9, v22, v23
	v_cvt_pk_bf16_f32 v10, v12, v13
	v_add_co_u32_e32 v12, vcc, s82, v144
	s_nop 0
	v_lshl_add_u64 v[16:17], v[144:145], 0, s[44:45]
	v_addc_co_u32_e32 v13, vcc, 0, v145, vcc
	s_andn2_b64 vcc, exec, s[4:5]
	s_mov_b64 s[4:5], -1
	v_cvt_pk_bf16_f32 v11, v14, v15
	global_store_dwordx4 v[12:13], v[8:11], off sc1
	v_cvt_pk_bf16_f32 v4, v4, v5
	v_cvt_pk_bf16_f32 v5, v6, v7
	v_cvt_pk_bf16_f32 v6, v0, v1
	v_cvt_pk_bf16_f32 v7, v2, v3
	global_store_dwordx4 v[16:17], v[4:7], off offset:256 sc1
	s_cbranch_vccnz .LBB0_593
	s_andn2_b64 vcc, exec, s[8:9]
	s_cbranch_vccnz .LBB0_592
	s_barrier
	s_branch .LBB0_592

.LBB0_807:
	v_lshl_add_u32 v152, s82, 8, v146
	v_lshl_or_b32 v144, s83, 8, v148
	v_ashrrev_i32_e32 v145, 31, v144
	v_ashrrev_i32_e32 v153, 31, v152
	v_lshl_add_u64 v[154:155], v[144:145], 1, s[24:25]
	v_lshlrev_b64 v[144:145], 11, v[152:153]
	v_lshl_add_u64 v[144:145], v[154:155], 0, v[144:145]
	s_nop 15
	s_nop 7
	v_cvt_pk_bf16_f32 v124, v124, v125
	v_cvt_pk_bf16_f32 v125, v126, v127
	v_cvt_pk_bf16_f32 v126, v120, v121
	v_cvt_pk_bf16_f32 v127, v122, v123
	global_store_dwordx4 v[144:145], v[124:127], off sc1
	v_cvt_pk_bf16_f32 v112, v112, v113
	v_cvt_pk_bf16_f32 v113, v114, v115
	v_cvt_pk_bf16_f32 v114, v104, v105
	v_or_b32_e32 v104, 16, v152
	v_ashrrev_i32_e32 v105, 31, v104
	v_lshlrev_b64 v[104:105], 11, v[104:105]
	v_cvt_pk_bf16_f32 v115, v106, v107
	global_store_dwordx4 v[144:145], v[112:115], off offset:256 sc1
	s_nop 1
	v_lshl_add_u64 v[112:113], v[154:155], 0, v[104:105]
	v_cvt_pk_bf16_f32 v104, v116, v117
	v_cvt_pk_bf16_f32 v105, v118, v119
	v_cvt_pk_bf16_f32 v106, v108, v109
	v_cvt_pk_bf16_f32 v107, v110, v111
	global_store_dwordx4 v[112:113], v[104:107], off sc1
	v_cvt_pk_bf16_f32 v96, v96, v97
	v_cvt_pk_bf16_f32 v97, v98, v99
	v_cvt_pk_bf16_f32 v98, v88, v89
	v_or_b32_e32 v88, 32, v152
	v_ashrrev_i32_e32 v89, 31, v88
	v_lshlrev_b64 v[88:89], 11, v[88:89]
	v_cvt_pk_bf16_f32 v99, v90, v91
	global_store_dwordx4 v[112:113], v[96:99], off offset:256 sc1
	s_nop 1
	v_lshl_add_u64 v[96:97], v[154:155], 0, v[88:89]
	v_cvt_pk_bf16_f32 v88, v100, v101
	v_cvt_pk_bf16_f32 v89, v102, v103
	v_cvt_pk_bf16_f32 v90, v92, v93
	v_cvt_pk_bf16_f32 v91, v94, v95
	global_store_dwordx4 v[96:97], v[88:91], off sc1
	v_cvt_pk_bf16_f32 v80, v80, v81
	v_cvt_pk_bf16_f32 v81, v82, v83
	v_cvt_pk_bf16_f32 v82, v72, v73
	v_or_b32_e32 v72, 48, v152
	v_ashrrev_i32_e32 v73, 31, v72
	v_lshlrev_b64 v[72:73], 11, v[72:73]
	v_cvt_pk_bf16_f32 v83, v74, v75
	global_store_dwordx4 v[96:97], v[80:83], off offset:256 sc1
	s_nop 1
	v_lshl_add_u64 v[80:81], v[154:155], 0, v[72:73]
	v_cvt_pk_bf16_f32 v72, v84, v85
	v_cvt_pk_bf16_f32 v73, v86, v87
	v_cvt_pk_bf16_f32 v74, v76, v77
	v_cvt_pk_bf16_f32 v75, v78, v79
	global_store_dwordx4 v[80:81], v[72:75], off sc1
	v_cvt_pk_bf16_f32 v68, v68, v69
	v_cvt_pk_bf16_f32 v69, v70, v71
	v_cvt_pk_bf16_f32 v70, v64, v65
	v_cvt_pk_bf16_f32 v71, v66, v67
	global_store_dwordx4 v[80:81], v[68:71], off offset:256 sc1
	v_cvt_pk_bf16_f32 v60, v60, v61
	v_cvt_pk_bf16_f32 v61, v62, v63
	v_cvt_pk_bf16_f32 v62, v56, v57
	v_add_co_u32_e32 v56, vcc, s72, v144
	v_lshl_add_u64 v[64:65], v[144:145], 0, s[30:31]
	s_nop 0
	v_addc_co_u32_e32 v57, vcc, 0, v145, vcc
	v_cvt_pk_bf16_f32 v63, v58, v59
	global_store_dwordx4 v[56:57], v[60:63], off sc1
	v_cvt_pk_bf16_f32 v48, v48, v49
	v_cvt_pk_bf16_f32 v49, v50, v51
	v_cvt_pk_bf16_f32 v50, v40, v41
	v_cvt_pk_bf16_f32 v51, v42, v43
	global_store_dwordx4 v[64:65], v[48:51], off offset:256 sc1
	v_cvt_pk_bf16_f32 v40, v52, v53
	v_cvt_pk_bf16_f32 v41, v54, v55
	v_cvt_pk_bf16_f32 v42, v44, v45
	v_add_co_u32_e32 v44, vcc, s73, v144
	s_nop 0
	v_lshl_add_u64 v[48:49], v[144:145], 0, s[36:37]
	v_addc_co_u32_e32 v45, vcc, 0, v145, vcc
	v_cvt_pk_bf16_f32 v43, v46, v47
	global_store_dwordx4 v[44:45], v[40:43], off sc1
	v_cvt_pk_bf16_f32 v32, v32, v33
	v_cvt_pk_bf16_f32 v33, v34, v35
	v_cvt_pk_bf16_f32 v34, v24, v25
	v_cvt_pk_bf16_f32 v35, v26, v27
	global_store_dwordx4 v[48:49], v[32:35], off offset:256 sc1
	v_cvt_pk_bf16_f32 v24, v36, v37
	v_cvt_pk_bf16_f32 v25, v38, v39
	v_cvt_pk_bf16_f32 v26, v28, v29
	v_add_co_u32_e32 v28, vcc, s74, v144
	s_nop 0
	v_lshl_add_u64 v[32:33], v[144:145], 0, s[44:45]
	v_addc_co_u32_e32 v29, vcc, 0, v145, vcc
	v_cvt_pk_bf16_f32 v27, v30, v31
	global_store_dwordx4 v[28:29], v[24:27], off sc1
	v_cvt_pk_bf16_f32 v16, v16, v17
	v_cvt_pk_bf16_f32 v17, v18, v19
	v_cvt_pk_bf16_f32 v18, v8, v9
	v_cvt_pk_bf16_f32 v19, v10, v11
	global_store_dwordx4 v[32:33], v[16:19], off offset:256 sc1
	v_cvt_pk_bf16_f32 v8, v20, v21
	v_cvt_pk_bf16_f32 v9, v22, v23
	v_cvt_pk_bf16_f32 v10, v12, v13
	v_add_co_u32_e32 v12, vcc, s75, v144
	s_nop 0
	v_lshl_add_u64 v[16:17], v[144:145], 0, s[46:47]
	v_addc_co_u32_e32 v13, vcc, 0, v145, vcc
	s_and_b64 vcc, exec, s[10:11]
	s_mov_b64 s[10:11], -1
	v_cvt_pk_bf16_f32 v11, v14, v15
	global_store_dwordx4 v[12:13], v[8:11], off sc1
	v_cvt_pk_bf16_f32 v4, v4, v5
	v_cvt_pk_bf16_f32 v5, v6, v7
	v_cvt_pk_bf16_f32 v6, v0, v1
	v_cvt_pk_bf16_f32 v7, v2, v3
	global_store_dwordx4 v[16:17], v[4:7], off offset:256 sc1
	s_cbranch_vccnz .LBB0_792
	s_andn2_b64 vcc, exec, s[0:1]
	s_cbranch_vccnz .LBB0_791
	s_barrier
	s_branch .LBB0_791

.LBB0_1034:
	v_lshl_add_u32 v152, s84, 8, v146
	v_lshl_or_b32 v144, s85, 8, v148
	v_ashrrev_i32_e32 v145, 31, v144
	v_ashrrev_i32_e32 v153, 31, v152
	v_lshl_add_u64 v[154:155], v[144:145], 1, s[24:25]
	v_lshlrev_b64 v[144:145], 11, v[152:153]
	v_lshl_add_u64 v[144:145], v[154:155], 0, v[144:145]
	s_nop 15
	s_nop 7
	v_cvt_pk_bf16_f32 v124, v124, v125
	v_cvt_pk_bf16_f32 v125, v126, v127
	v_cvt_pk_bf16_f32 v126, v120, v121
	v_cvt_pk_bf16_f32 v127, v122, v123
	global_store_dwordx4 v[144:145], v[124:127], off sc1
	v_cvt_pk_bf16_f32 v112, v112, v113
	v_cvt_pk_bf16_f32 v113, v114, v115
	v_cvt_pk_bf16_f32 v114, v104, v105
	v_or_b32_e32 v104, 16, v152
	v_ashrrev_i32_e32 v105, 31, v104
	v_lshlrev_b64 v[104:105], 11, v[104:105]
	v_cvt_pk_bf16_f32 v115, v106, v107
	global_store_dwordx4 v[144:145], v[112:115], off offset:256 sc1
	s_nop 1
	v_lshl_add_u64 v[112:113], v[154:155], 0, v[104:105]
	v_cvt_pk_bf16_f32 v104, v116, v117
	v_cvt_pk_bf16_f32 v105, v118, v119
	v_cvt_pk_bf16_f32 v106, v108, v109
	v_cvt_pk_bf16_f32 v107, v110, v111
	global_store_dwordx4 v[112:113], v[104:107], off sc1
	v_cvt_pk_bf16_f32 v96, v96, v97
	v_cvt_pk_bf16_f32 v97, v98, v99
	v_cvt_pk_bf16_f32 v98, v88, v89
	v_or_b32_e32 v88, 32, v152
	v_ashrrev_i32_e32 v89, 31, v88
	v_lshlrev_b64 v[88:89], 11, v[88:89]
	v_cvt_pk_bf16_f32 v99, v90, v91
	global_store_dwordx4 v[112:113], v[96:99], off offset:256 sc1
	s_nop 1
	v_lshl_add_u64 v[96:97], v[154:155], 0, v[88:89]
	v_cvt_pk_bf16_f32 v88, v100, v101
	v_cvt_pk_bf16_f32 v89, v102, v103
	v_cvt_pk_bf16_f32 v90, v92, v93
	v_cvt_pk_bf16_f32 v91, v94, v95
	global_store_dwordx4 v[96:97], v[88:91], off sc1
	v_cvt_pk_bf16_f32 v80, v80, v81
	v_cvt_pk_bf16_f32 v81, v82, v83
	v_cvt_pk_bf16_f32 v82, v72, v73
	v_or_b32_e32 v72, 48, v152
	v_ashrrev_i32_e32 v73, 31, v72
	v_lshlrev_b64 v[72:73], 11, v[72:73]
	v_cvt_pk_bf16_f32 v83, v74, v75
	global_store_dwordx4 v[96:97], v[80:83], off offset:256 sc1
	s_nop 1
	v_lshl_add_u64 v[80:81], v[154:155], 0, v[72:73]
	v_cvt_pk_bf16_f32 v72, v84, v85
	v_cvt_pk_bf16_f32 v73, v86, v87
	v_cvt_pk_bf16_f32 v74, v76, v77
	v_cvt_pk_bf16_f32 v75, v78, v79
	global_store_dwordx4 v[80:81], v[72:75], off sc1
	v_cvt_pk_bf16_f32 v68, v68, v69
	v_cvt_pk_bf16_f32 v69, v70, v71
	v_cvt_pk_bf16_f32 v70, v64, v65
	v_cvt_pk_bf16_f32 v71, v66, v67
	global_store_dwordx4 v[80:81], v[68:71], off offset:256 sc1
	v_cvt_pk_bf16_f32 v60, v60, v61
	v_cvt_pk_bf16_f32 v61, v62, v63
	v_cvt_pk_bf16_f32 v62, v56, v57
	v_add_co_u32_e32 v56, vcc, s74, v144
	v_lshl_add_u64 v[64:65], v[144:145], 0, s[36:37]
	s_nop 0
	v_addc_co_u32_e32 v57, vcc, 0, v145, vcc
	v_cvt_pk_bf16_f32 v63, v58, v59
	global_store_dwordx4 v[56:57], v[60:63], off sc1
	v_cvt_pk_bf16_f32 v48, v48, v49
	v_cvt_pk_bf16_f32 v49, v50, v51
	v_cvt_pk_bf16_f32 v50, v40, v41
	v_cvt_pk_bf16_f32 v51, v42, v43
	global_store_dwordx4 v[64:65], v[48:51], off offset:256 sc1
	v_cvt_pk_bf16_f32 v40, v52, v53
	v_cvt_pk_bf16_f32 v41, v54, v55
	v_cvt_pk_bf16_f32 v42, v44, v45
	v_add_co_u32_e32 v44, vcc, s75, v144
	s_nop 0
	v_lshl_add_u64 v[48:49], v[144:145], 0, s[44:45]
	v_addc_co_u32_e32 v45, vcc, 0, v145, vcc
	v_cvt_pk_bf16_f32 v43, v46, v47
	global_store_dwordx4 v[44:45], v[40:43], off sc1
	v_cvt_pk_bf16_f32 v32, v32, v33
	v_cvt_pk_bf16_f32 v33, v34, v35
	v_cvt_pk_bf16_f32 v34, v24, v25
	v_cvt_pk_bf16_f32 v35, v26, v27
	global_store_dwordx4 v[48:49], v[32:35], off offset:256 sc1
	v_cvt_pk_bf16_f32 v24, v36, v37
	v_cvt_pk_bf16_f32 v25, v38, v39
	v_cvt_pk_bf16_f32 v26, v28, v29
	v_add_co_u32_e32 v28, vcc, s76, v144
	s_nop 0
	v_lshl_add_u64 v[32:33], v[144:145], 0, s[46:47]
	v_addc_co_u32_e32 v29, vcc, 0, v145, vcc
	v_cvt_pk_bf16_f32 v27, v30, v31
	global_store_dwordx4 v[28:29], v[24:27], off sc1
	v_cvt_pk_bf16_f32 v16, v16, v17
	v_cvt_pk_bf16_f32 v17, v18, v19
	v_cvt_pk_bf16_f32 v18, v8, v9
	v_cvt_pk_bf16_f32 v19, v10, v11
	global_store_dwordx4 v[32:33], v[16:19], off offset:256 sc1
	v_cvt_pk_bf16_f32 v8, v20, v21
	v_cvt_pk_bf16_f32 v9, v22, v23
	v_cvt_pk_bf16_f32 v10, v12, v13
	v_add_co_u32_e32 v12, vcc, s77, v144
	s_nop 0
	v_lshl_add_u64 v[16:17], v[144:145], 0, s[48:49]
	v_addc_co_u32_e32 v13, vcc, 0, v145, vcc
	s_and_b64 vcc, exec, s[10:11]
	s_mov_b64 s[10:11], -1
	v_cvt_pk_bf16_f32 v11, v14, v15
	global_store_dwordx4 v[12:13], v[8:11], off sc1
	v_cvt_pk_bf16_f32 v4, v4, v5
	v_cvt_pk_bf16_f32 v5, v6, v7
	v_cvt_pk_bf16_f32 v6, v0, v1
	v_cvt_pk_bf16_f32 v7, v2, v3
	global_store_dwordx4 v[16:17], v[4:7], off offset:256 sc1
	s_cbranch_vccnz .LBB0_1019
	s_andn2_b64 vcc, exec, s[0:1]
	s_cbranch_vccnz .LBB0_1018
	s_barrier
	s_branch .LBB0_1018

.LBB0_1165:
	s_lshl_b32 s49, s59, 8
	s_or_b32 s49, s49, s74
	v_lshl_add_u32 v152, s58, 8, v146
	s_ashr_i32 s58, s49, 6
	s_ashr_i32 s59, s58, 31
	s_lshl_b64 s[60:61], s[58:59], 22
	s_cmp_lt_i32 s58, 16
	s_cselect_b64 vcc, -1, 0
	v_cndmask_b32_e32 v156, 1.0, v151, vcc
	v_pk_mul_f32 v[124:125], v[156:157], v[124:125] op_sel_hi:[0,1]
	v_ashrrev_i32_e32 v153, 31, v152
	v_lshl_add_u64 v[154:155], v[136:137], 0, s[60:61]
	v_pk_mul_f32 v[126:127], v[156:157], v[126:127] op_sel_hi:[0,1]
	v_pk_mul_f32 v[158:159], v[156:157], v[122:123] op_sel_hi:[0,1]
	v_pk_mul_f32 v[122:123], v[156:157], v[120:121] op_sel_hi:[0,1]
	v_cvt_pk_bf16_f32 v120, v124, v125
	v_lshlrev_b64 v[124:125], 7, v[152:153]
	v_cvt_pk_bf16_f32 v121, v126, v127
	v_lshl_add_u64 v[126:127], v[154:155], 0, v[124:125]
	v_pk_mul_f32 v[116:117], v[156:157], v[116:117] op_sel_hi:[0,1]
	v_cvt_pk_bf16_f32 v122, v122, v123
	v_cvt_pk_bf16_f32 v123, v158, v159
	global_store_dwordx4 v[126:127], v[120:123], off sc1
	v_pk_mul_f32 v[118:119], v[156:157], v[118:119] op_sel_hi:[0,1]
	v_pk_mul_f32 v[108:109], v[156:157], v[108:109] op_sel_hi:[0,1]
	v_pk_mul_f32 v[120:121], v[156:157], v[114:115] op_sel_hi:[0,1]
	v_pk_mul_f32 v[114:115], v[156:157], v[112:113] op_sel_hi:[0,1]
	v_cvt_pk_bf16_f32 v112, v116, v117
	v_or_b32_e32 v116, 16, v152
	v_ashrrev_i32_e32 v117, 31, v116
	v_lshlrev_b64 v[116:117], 7, v[116:117]
	v_cvt_pk_bf16_f32 v113, v118, v119
	v_lshl_add_u64 v[118:119], v[154:155], 0, v[116:117]
	v_cvt_pk_bf16_f32 v114, v114, v115
	v_cvt_pk_bf16_f32 v115, v120, v121
	global_store_dwordx4 v[118:119], v[112:115], off sc1
	v_pk_mul_f32 v[110:111], v[156:157], v[110:111] op_sel_hi:[0,1]
	v_pk_mul_f32 v[100:101], v[156:157], v[100:101] op_sel_hi:[0,1]
	v_pk_mul_f32 v[112:113], v[156:157], v[106:107] op_sel_hi:[0,1]
	v_pk_mul_f32 v[106:107], v[156:157], v[104:105] op_sel_hi:[0,1]
	v_cvt_pk_bf16_f32 v104, v108, v109
	v_or_b32_e32 v108, 32, v152
	v_ashrrev_i32_e32 v109, 31, v108
	v_lshlrev_b64 v[108:109], 7, v[108:109]
	v_cvt_pk_bf16_f32 v105, v110, v111
	v_lshl_add_u64 v[110:111], v[154:155], 0, v[108:109]
	v_cvt_pk_bf16_f32 v106, v106, v107
	v_cvt_pk_bf16_f32 v107, v112, v113
	global_store_dwordx4 v[110:111], v[104:107], off sc1
	v_pk_mul_f32 v[102:103], v[156:157], v[102:103] op_sel_hi:[0,1]
	v_pk_mul_f32 v[92:93], v[156:157], v[92:93] op_sel_hi:[0,1]
	v_pk_mul_f32 v[104:105], v[156:157], v[98:99] op_sel_hi:[0,1]
	v_pk_mul_f32 v[98:99], v[156:157], v[96:97] op_sel_hi:[0,1]
	v_cvt_pk_bf16_f32 v96, v100, v101
	v_or_b32_e32 v100, 48, v152
	v_ashrrev_i32_e32 v101, 31, v100
	v_lshlrev_b64 v[100:101], 7, v[100:101]
	v_cvt_pk_bf16_f32 v97, v102, v103
	v_lshl_add_u64 v[102:103], v[154:155], 0, v[100:101]
	v_cvt_pk_bf16_f32 v98, v98, v99
	v_cvt_pk_bf16_f32 v99, v104, v105
	global_store_dwordx4 v[102:103], v[96:99], off sc1
	v_pk_mul_f32 v[94:95], v[156:157], v[94:95] op_sel_hi:[0,1]
	v_pk_mul_f32 v[84:85], v[156:157], v[84:85] op_sel_hi:[0,1]
	v_pk_mul_f32 v[96:97], v[156:157], v[90:91] op_sel_hi:[0,1]
	v_pk_mul_f32 v[90:91], v[156:157], v[88:89] op_sel_hi:[0,1]
	v_cvt_pk_bf16_f32 v88, v92, v93
	v_lshl_add_u64 v[92:93], v[124:125], 0, s[18:19]
	v_cvt_pk_bf16_f32 v89, v94, v95
	v_lshl_add_u64 v[94:95], v[154:155], 0, v[92:93]
	v_cvt_pk_bf16_f32 v90, v90, v91
	v_cvt_pk_bf16_f32 v91, v96, v97
	global_store_dwordx4 v[94:95], v[88:91], off sc1
	v_pk_mul_f32 v[86:87], v[156:157], v[86:87] op_sel_hi:[0,1]
	s_or_b32 s58, s58, 2
	v_pk_mul_f32 v[88:89], v[156:157], v[82:83] op_sel_hi:[0,1]
	v_pk_mul_f32 v[82:83], v[156:157], v[80:81] op_sel_hi:[0,1]
	v_cvt_pk_bf16_f32 v80, v84, v85
	v_lshl_add_u64 v[84:85], v[124:125], 0, s[36:37]
	v_cvt_pk_bf16_f32 v81, v86, v87
	v_lshl_add_u64 v[86:87], v[154:155], 0, v[84:85]
	v_pk_mul_f32 v[76:77], v[156:157], v[76:77] op_sel_hi:[0,1]
	s_ashr_i32 s59, s58, 31
	v_cvt_pk_bf16_f32 v82, v82, v83
	v_cvt_pk_bf16_f32 v83, v88, v89
	global_store_dwordx4 v[86:87], v[80:83], off sc1
	v_pk_mul_f32 v[78:79], v[156:157], v[78:79] op_sel_hi:[0,1]
	s_lshl_b64 s[60:61], s[58:59], 22
	v_pk_mul_f32 v[80:81], v[156:157], v[74:75] op_sel_hi:[0,1]
	v_pk_mul_f32 v[74:75], v[156:157], v[72:73] op_sel_hi:[0,1]
	v_cvt_pk_bf16_f32 v72, v76, v77
	v_lshl_add_u64 v[76:77], v[124:125], 0, s[44:45]
	v_cvt_pk_bf16_f32 v73, v78, v79
	v_lshl_add_u64 v[78:79], v[154:155], 0, v[76:77]
	v_pk_mul_f32 v[60:61], v[156:157], v[60:61] op_sel_hi:[0,1]
	s_cmp_lt_i32 s58, 16
	v_cvt_pk_bf16_f32 v74, v74, v75
	v_cvt_pk_bf16_f32 v75, v80, v81
	global_store_dwordx4 v[78:79], v[72:75], off sc1
	v_pk_mul_f32 v[62:63], v[156:157], v[62:63] op_sel_hi:[0,1]
	s_cselect_b64 vcc, -1, 0
	v_pk_mul_f32 v[72:73], v[156:157], v[58:59] op_sel_hi:[0,1]
	v_pk_mul_f32 v[58:59], v[156:157], v[56:57] op_sel_hi:[0,1]
	v_cvt_pk_bf16_f32 v56, v60, v61
	v_lshl_add_u64 v[60:61], v[124:125], 0, s[46:47]
	v_cvt_pk_bf16_f32 v57, v62, v63
	v_cvt_pk_bf16_f32 v58, v58, v59
	v_cvt_pk_bf16_f32 v59, v72, v73
	v_lshl_add_u64 v[62:63], v[154:155], 0, v[60:61]
	v_cndmask_b32_e32 v72, 1.0, v151, vcc
	global_store_dwordx4 v[62:63], v[56:59], off sc1
	v_lshl_add_u64 v[62:63], v[136:137], 0, s[60:61]
	v_pk_mul_f32 v[64:65], v[72:73], v[64:65] op_sel_hi:[0,1]
	v_pk_mul_f32 v[58:59], v[72:73], v[70:71] op_sel_hi:[0,1]
	v_pk_mul_f32 v[56:57], v[72:73], v[68:69] op_sel_hi:[0,1]
	v_cvt_pk_bf16_f32 v56, v56, v57
	v_cvt_pk_bf16_f32 v57, v58, v59
	v_cvt_pk_bf16_f32 v58, v64, v65
	v_lshl_add_u64 v[64:65], v[62:63], 0, v[124:125]
	v_pk_mul_f32 v[52:53], v[72:73], v[52:53] op_sel_hi:[0,1]
	v_pk_mul_f32 v[66:67], v[72:73], v[66:67] op_sel_hi:[0,1]
	v_cvt_pk_bf16_f32 v59, v66, v67
	global_store_dwordx4 v[64:65], v[56:59], off sc1
	v_pk_mul_f32 v[54:55], v[72:73], v[54:55] op_sel_hi:[0,1]
	v_pk_mul_f32 v[44:45], v[72:73], v[44:45] op_sel_hi:[0,1]
	v_pk_mul_f32 v[56:57], v[72:73], v[50:51] op_sel_hi:[0,1]
	v_pk_mul_f32 v[50:51], v[72:73], v[48:49] op_sel_hi:[0,1]
	v_cvt_pk_bf16_f32 v48, v52, v53
	v_cvt_pk_bf16_f32 v49, v54, v55
	v_lshl_add_u64 v[52:53], v[62:63], 0, v[116:117]
	v_cvt_pk_bf16_f32 v50, v50, v51
	v_cvt_pk_bf16_f32 v51, v56, v57
	global_store_dwordx4 v[52:53], v[48:51], off sc1
	v_pk_mul_f32 v[46:47], v[72:73], v[46:47] op_sel_hi:[0,1]
	v_pk_mul_f32 v[36:37], v[72:73], v[36:37] op_sel_hi:[0,1]
	v_pk_mul_f32 v[48:49], v[72:73], v[42:43] op_sel_hi:[0,1]
	v_pk_mul_f32 v[42:43], v[72:73], v[40:41] op_sel_hi:[0,1]
	v_cvt_pk_bf16_f32 v40, v44, v45
	v_cvt_pk_bf16_f32 v41, v46, v47
	v_lshl_add_u64 v[44:45], v[62:63], 0, v[108:109]
	v_cvt_pk_bf16_f32 v42, v42, v43
	v_cvt_pk_bf16_f32 v43, v48, v49
	global_store_dwordx4 v[44:45], v[40:43], off sc1
	v_pk_mul_f32 v[38:39], v[72:73], v[38:39] op_sel_hi:[0,1]
	v_pk_mul_f32 v[28:29], v[72:73], v[28:29] op_sel_hi:[0,1]
	v_pk_mul_f32 v[40:41], v[72:73], v[34:35] op_sel_hi:[0,1]
	v_pk_mul_f32 v[34:35], v[72:73], v[32:33] op_sel_hi:[0,1]
	v_cvt_pk_bf16_f32 v32, v36, v37
	v_cvt_pk_bf16_f32 v33, v38, v39
	v_lshl_add_u64 v[36:37], v[62:63], 0, v[100:101]
	v_cvt_pk_bf16_f32 v34, v34, v35
	v_cvt_pk_bf16_f32 v35, v40, v41
	global_store_dwordx4 v[36:37], v[32:35], off sc1
	v_pk_mul_f32 v[30:31], v[72:73], v[30:31] op_sel_hi:[0,1]
	v_pk_mul_f32 v[20:21], v[72:73], v[20:21] op_sel_hi:[0,1]
	v_pk_mul_f32 v[32:33], v[72:73], v[26:27] op_sel_hi:[0,1]
	v_pk_mul_f32 v[26:27], v[72:73], v[24:25] op_sel_hi:[0,1]
	v_cvt_pk_bf16_f32 v24, v28, v29
	v_cvt_pk_bf16_f32 v25, v30, v31
	v_lshl_add_u64 v[28:29], v[62:63], 0, v[92:93]
	v_cvt_pk_bf16_f32 v26, v26, v27
	v_cvt_pk_bf16_f32 v27, v32, v33
	global_store_dwordx4 v[28:29], v[24:27], off sc1
	v_pk_mul_f32 v[22:23], v[72:73], v[22:23] op_sel_hi:[0,1]
	v_pk_mul_f32 v[12:13], v[72:73], v[12:13] op_sel_hi:[0,1]
	v_pk_mul_f32 v[24:25], v[72:73], v[18:19] op_sel_hi:[0,1]
	v_pk_mul_f32 v[18:19], v[72:73], v[16:17] op_sel_hi:[0,1]
	v_cvt_pk_bf16_f32 v16, v20, v21
	v_cvt_pk_bf16_f32 v17, v22, v23
	v_lshl_add_u64 v[20:21], v[62:63], 0, v[84:85]
	v_cvt_pk_bf16_f32 v18, v18, v19
	v_cvt_pk_bf16_f32 v19, v24, v25
	global_store_dwordx4 v[20:21], v[16:19], off sc1
	v_pk_mul_f32 v[14:15], v[72:73], v[14:15] op_sel_hi:[0,1]
	v_pk_mul_f32 v[4:5], v[72:73], v[4:5] op_sel_hi:[0,1]
	v_pk_mul_f32 v[16:17], v[72:73], v[10:11] op_sel_hi:[0,1]
	v_pk_mul_f32 v[10:11], v[72:73], v[8:9] op_sel_hi:[0,1]
	v_cvt_pk_bf16_f32 v8, v12, v13
	v_cvt_pk_bf16_f32 v9, v14, v15
	v_lshl_add_u64 v[12:13], v[62:63], 0, v[76:77]
	v_cvt_pk_bf16_f32 v10, v10, v11
	v_cvt_pk_bf16_f32 v11, v16, v17
	global_store_dwordx4 v[12:13], v[8:11], off sc1
	s_andn2_b64 vcc, exec, s[10:11]
	s_mov_b64 s[10:11], -1
	v_pk_mul_f32 v[8:9], v[72:73], v[2:3] op_sel_hi:[0,1]
	v_pk_mul_f32 v[2:3], v[72:73], v[0:1] op_sel_hi:[0,1]
	v_cvt_pk_bf16_f32 v0, v4, v5
	v_lshl_add_u64 v[4:5], v[62:63], 0, v[60:61]
	v_pk_mul_f32 v[6:7], v[72:73], v[6:7] op_sel_hi:[0,1]
	v_cvt_pk_bf16_f32 v1, v6, v7
	v_cvt_pk_bf16_f32 v2, v2, v3
	v_cvt_pk_bf16_f32 v3, v8, v9
	global_store_dwordx4 v[4:5], v[0:3], off sc1
	s_cbranch_vccnz .LBB0_1154
	s_andn2_b64 vcc, exec, s[0:1]
	s_cbranch_vccnz .LBB0_1153
	s_barrier
	s_branch .LBB0_1153

.LBB0_1314:
	v_lshl_add_u32 v152, s54, 8, v146
	v_lshl_or_b32 v144, s77, 8, v148
	v_ashrrev_i32_e32 v145, 31, v144
	v_ashrrev_i32_e32 v153, 31, v152
	v_lshl_add_u64 v[154:155], v[144:145], 1, s[24:25]
	v_lshlrev_b64 v[144:145], 11, v[152:153]
	v_lshl_add_u64 v[144:145], v[154:155], 0, v[144:145]
	s_nop 15
	s_nop 7
	v_cvt_pk_bf16_f32 v124, v124, v125
	v_cvt_pk_bf16_f32 v125, v126, v127
	v_cvt_pk_bf16_f32 v126, v120, v121
	v_cvt_pk_bf16_f32 v127, v122, v123
	global_store_dwordx4 v[144:145], v[124:127], off sc1
	v_cvt_pk_bf16_f32 v112, v112, v113
	v_cvt_pk_bf16_f32 v113, v114, v115
	v_cvt_pk_bf16_f32 v114, v104, v105
	v_or_b32_e32 v104, 16, v152
	v_ashrrev_i32_e32 v105, 31, v104
	v_lshlrev_b64 v[104:105], 11, v[104:105]
	v_cvt_pk_bf16_f32 v115, v106, v107
	global_store_dwordx4 v[144:145], v[112:115], off offset:256 sc1
	s_nop 1
	v_lshl_add_u64 v[112:113], v[154:155], 0, v[104:105]
	v_cvt_pk_bf16_f32 v104, v116, v117
	v_cvt_pk_bf16_f32 v105, v118, v119
	v_cvt_pk_bf16_f32 v106, v108, v109
	v_cvt_pk_bf16_f32 v107, v110, v111
	global_store_dwordx4 v[112:113], v[104:107], off sc1
	v_cvt_pk_bf16_f32 v96, v96, v97
	v_cvt_pk_bf16_f32 v97, v98, v99
	v_cvt_pk_bf16_f32 v98, v88, v89
	v_or_b32_e32 v88, 32, v152
	v_ashrrev_i32_e32 v89, 31, v88
	v_lshlrev_b64 v[88:89], 11, v[88:89]
	v_cvt_pk_bf16_f32 v99, v90, v91
	global_store_dwordx4 v[112:113], v[96:99], off offset:256 sc1
	s_nop 1
	v_lshl_add_u64 v[96:97], v[154:155], 0, v[88:89]
	v_cvt_pk_bf16_f32 v88, v100, v101
	v_cvt_pk_bf16_f32 v89, v102, v103
	v_cvt_pk_bf16_f32 v90, v92, v93
	v_cvt_pk_bf16_f32 v91, v94, v95
	global_store_dwordx4 v[96:97], v[88:91], off sc1
	v_cvt_pk_bf16_f32 v80, v80, v81
	v_cvt_pk_bf16_f32 v81, v82, v83
	v_cvt_pk_bf16_f32 v82, v72, v73
	v_or_b32_e32 v72, 48, v152
	v_ashrrev_i32_e32 v73, 31, v72
	v_lshlrev_b64 v[72:73], 11, v[72:73]
	v_cvt_pk_bf16_f32 v83, v74, v75
	global_store_dwordx4 v[96:97], v[80:83], off offset:256 sc1
	s_nop 1
	v_lshl_add_u64 v[80:81], v[154:155], 0, v[72:73]
	v_cvt_pk_bf16_f32 v72, v84, v85
	v_cvt_pk_bf16_f32 v73, v86, v87
	v_cvt_pk_bf16_f32 v74, v76, v77
	v_cvt_pk_bf16_f32 v75, v78, v79
	global_store_dwordx4 v[80:81], v[72:75], off sc1
	v_cvt_pk_bf16_f32 v68, v68, v69
	v_cvt_pk_bf16_f32 v69, v70, v71
	v_cvt_pk_bf16_f32 v70, v64, v65
	v_cvt_pk_bf16_f32 v71, v66, v67
	global_store_dwordx4 v[80:81], v[68:71], off offset:256 sc1
	v_cvt_pk_bf16_f32 v60, v60, v61
	v_cvt_pk_bf16_f32 v61, v62, v63
	v_cvt_pk_bf16_f32 v62, v56, v57
	v_add_co_u32_e32 v56, vcc, s73, v144
	v_lshl_add_u64 v[64:65], v[144:145], 0, s[0:1]
	s_nop 0
	v_addc_co_u32_e32 v57, vcc, 0, v145, vcc
	v_cvt_pk_bf16_f32 v63, v58, v59
	global_store_dwordx4 v[56:57], v[60:63], off sc1
	v_cvt_pk_bf16_f32 v48, v48, v49
	v_cvt_pk_bf16_f32 v49, v50, v51
	v_cvt_pk_bf16_f32 v50, v40, v41
	v_cvt_pk_bf16_f32 v51, v42, v43
	global_store_dwordx4 v[64:65], v[48:51], off offset:256 sc1
	v_cvt_pk_bf16_f32 v40, v52, v53
	v_cvt_pk_bf16_f32 v41, v54, v55
	v_cvt_pk_bf16_f32 v42, v44, v45
	v_add_co_u32_e32 v44, vcc, s74, v144
	s_nop 0
	v_lshl_add_u64 v[48:49], v[144:145], 0, s[30:31]
	v_addc_co_u32_e32 v45, vcc, 0, v145, vcc
	v_cvt_pk_bf16_f32 v43, v46, v47
	global_store_dwordx4 v[44:45], v[40:43], off sc1
	v_cvt_pk_bf16_f32 v32, v32, v33
	v_cvt_pk_bf16_f32 v33, v34, v35
	v_cvt_pk_bf16_f32 v34, v24, v25
	v_cvt_pk_bf16_f32 v35, v26, v27
	global_store_dwordx4 v[48:49], v[32:35], off offset:256 sc1
	v_cvt_pk_bf16_f32 v24, v36, v37
	v_cvt_pk_bf16_f32 v25, v38, v39
	v_cvt_pk_bf16_f32 v26, v28, v29
	v_add_co_u32_e32 v28, vcc, s75, v144
	s_nop 0
	v_lshl_add_u64 v[32:33], v[144:145], 0, s[36:37]
	v_addc_co_u32_e32 v29, vcc, 0, v145, vcc
	v_cvt_pk_bf16_f32 v27, v30, v31
	global_store_dwordx4 v[28:29], v[24:27], off sc1
	v_cvt_pk_bf16_f32 v16, v16, v17
	v_cvt_pk_bf16_f32 v17, v18, v19
	v_cvt_pk_bf16_f32 v18, v8, v9
	v_cvt_pk_bf16_f32 v19, v10, v11
	global_store_dwordx4 v[32:33], v[16:19], off offset:256 sc1
	v_cvt_pk_bf16_f32 v8, v20, v21
	v_cvt_pk_bf16_f32 v9, v22, v23
	v_cvt_pk_bf16_f32 v10, v12, v13
	v_add_co_u32_e32 v12, vcc, s76, v144
	s_nop 0
	v_lshl_add_u64 v[16:17], v[144:145], 0, s[44:45]
	v_addc_co_u32_e32 v13, vcc, 0, v145, vcc
	s_andn2_b64 vcc, exec, s[10:11]
	s_mov_b64 s[10:11], -1
	v_cvt_pk_bf16_f32 v11, v14, v15
	global_store_dwordx4 v[12:13], v[8:11], off sc1
	v_cvt_pk_bf16_f32 v4, v4, v5
	v_cvt_pk_bf16_f32 v5, v6, v7
	v_cvt_pk_bf16_f32 v6, v0, v1
	v_cvt_pk_bf16_f32 v7, v2, v3
	global_store_dwordx4 v[16:17], v[4:7], off offset:256 sc1
	s_cbranch_vccnz .LBB0_1303
	s_andn2_b64 vcc, exec, s[12:13]
	s_cbranch_vccnz .LBB0_1302
	s_barrier
	s_branch .LBB0_1302

.LBB0_1517:
	v_lshl_add_u32 v152, s72, 8, v146
	v_lshl_or_b32 v144, s73, 8, v148
	v_ashrrev_i32_e32 v145, 31, v144
	v_ashrrev_i32_e32 v153, 31, v152
	v_lshl_add_u64 v[154:155], v[144:145], 1, s[24:25]
	v_lshlrev_b64 v[144:145], 11, v[152:153]
	v_lshl_add_u64 v[144:145], v[154:155], 0, v[144:145]
	s_nop 15
	s_nop 7
	v_cvt_pk_bf16_f32 v124, v124, v125
	v_cvt_pk_bf16_f32 v125, v126, v127
	v_cvt_pk_bf16_f32 v126, v120, v121
	v_cvt_pk_bf16_f32 v127, v122, v123
	global_store_dwordx4 v[144:145], v[124:127], off sc1
	v_cvt_pk_bf16_f32 v112, v112, v113
	v_cvt_pk_bf16_f32 v113, v114, v115
	v_cvt_pk_bf16_f32 v114, v104, v105
	v_or_b32_e32 v104, 16, v152
	v_ashrrev_i32_e32 v105, 31, v104
	v_lshlrev_b64 v[104:105], 11, v[104:105]
	v_cvt_pk_bf16_f32 v115, v106, v107
	global_store_dwordx4 v[144:145], v[112:115], off offset:256 sc1
	s_nop 1
	v_lshl_add_u64 v[112:113], v[154:155], 0, v[104:105]
	v_cvt_pk_bf16_f32 v104, v116, v117
	v_cvt_pk_bf16_f32 v105, v118, v119
	v_cvt_pk_bf16_f32 v106, v108, v109
	v_cvt_pk_bf16_f32 v107, v110, v111
	global_store_dwordx4 v[112:113], v[104:107], off sc1
	v_cvt_pk_bf16_f32 v96, v96, v97
	v_cvt_pk_bf16_f32 v97, v98, v99
	v_cvt_pk_bf16_f32 v98, v88, v89
	v_or_b32_e32 v88, 32, v152
	v_ashrrev_i32_e32 v89, 31, v88
	v_lshlrev_b64 v[88:89], 11, v[88:89]
	v_cvt_pk_bf16_f32 v99, v90, v91
	global_store_dwordx4 v[112:113], v[96:99], off offset:256 sc1
	s_nop 1
	v_lshl_add_u64 v[96:97], v[154:155], 0, v[88:89]
	v_cvt_pk_bf16_f32 v88, v100, v101
	v_cvt_pk_bf16_f32 v89, v102, v103
	v_cvt_pk_bf16_f32 v90, v92, v93
	v_cvt_pk_bf16_f32 v91, v94, v95
	global_store_dwordx4 v[96:97], v[88:91], off sc1
	v_cvt_pk_bf16_f32 v80, v80, v81
	v_cvt_pk_bf16_f32 v81, v82, v83
	v_cvt_pk_bf16_f32 v82, v72, v73
	v_or_b32_e32 v72, 48, v152
	v_ashrrev_i32_e32 v73, 31, v72
	v_lshlrev_b64 v[72:73], 11, v[72:73]
	v_cvt_pk_bf16_f32 v83, v74, v75
	global_store_dwordx4 v[96:97], v[80:83], off offset:256 sc1
	s_nop 1
	v_lshl_add_u64 v[80:81], v[154:155], 0, v[72:73]
	v_cvt_pk_bf16_f32 v72, v84, v85
	v_cvt_pk_bf16_f32 v73, v86, v87
	v_cvt_pk_bf16_f32 v74, v76, v77
	v_cvt_pk_bf16_f32 v75, v78, v79
	global_store_dwordx4 v[80:81], v[72:75], off sc1
	v_cvt_pk_bf16_f32 v68, v68, v69
	v_cvt_pk_bf16_f32 v69, v70, v71
	v_cvt_pk_bf16_f32 v70, v64, v65
	v_cvt_pk_bf16_f32 v71, v66, v67
	global_store_dwordx4 v[80:81], v[68:71], off offset:256 sc1
	v_cvt_pk_bf16_f32 v60, v60, v61
	v_cvt_pk_bf16_f32 v61, v62, v63
	v_cvt_pk_bf16_f32 v62, v56, v57
	v_add_co_u32_e32 v56, vcc, s66, v144
	v_lshl_add_u64 v[64:65], v[144:145], 0, s[16:17]
	s_nop 0
	v_addc_co_u32_e32 v57, vcc, 0, v145, vcc
	v_cvt_pk_bf16_f32 v63, v58, v59
	global_store_dwordx4 v[56:57], v[60:63], off sc1
	v_cvt_pk_bf16_f32 v48, v48, v49
	v_cvt_pk_bf16_f32 v49, v50, v51
	v_cvt_pk_bf16_f32 v50, v40, v41
	v_cvt_pk_bf16_f32 v51, v42, v43
	global_store_dwordx4 v[64:65], v[48:51], off offset:256 sc1
	v_cvt_pk_bf16_f32 v40, v52, v53
	v_cvt_pk_bf16_f32 v41, v54, v55
	v_cvt_pk_bf16_f32 v42, v44, v45
	v_add_co_u32_e32 v44, vcc, s67, v144
	s_nop 0
	v_lshl_add_u64 v[48:49], v[144:145], 0, s[18:19]
	v_addc_co_u32_e32 v45, vcc, 0, v145, vcc
	v_cvt_pk_bf16_f32 v43, v46, v47
	global_store_dwordx4 v[44:45], v[40:43], off sc1
	v_cvt_pk_bf16_f32 v32, v32, v33
	v_cvt_pk_bf16_f32 v33, v34, v35
	v_cvt_pk_bf16_f32 v34, v24, v25
	v_cvt_pk_bf16_f32 v35, v26, v27
	global_store_dwordx4 v[48:49], v[32:35], off offset:256 sc1
	v_cvt_pk_bf16_f32 v24, v36, v37
	v_cvt_pk_bf16_f32 v25, v38, v39
	v_cvt_pk_bf16_f32 v26, v28, v29
	v_add_co_u32_e32 v28, vcc, s68, v144
	s_nop 0
	v_lshl_add_u64 v[32:33], v[144:145], 0, s[30:31]
	v_addc_co_u32_e32 v29, vcc, 0, v145, vcc
	v_cvt_pk_bf16_f32 v27, v30, v31
	global_store_dwordx4 v[28:29], v[24:27], off sc1
	v_cvt_pk_bf16_f32 v16, v16, v17
	v_cvt_pk_bf16_f32 v17, v18, v19
	v_cvt_pk_bf16_f32 v18, v8, v9
	v_cvt_pk_bf16_f32 v19, v10, v11
	global_store_dwordx4 v[32:33], v[16:19], off offset:256 sc1
	v_cvt_pk_bf16_f32 v8, v20, v21
	v_cvt_pk_bf16_f32 v9, v22, v23
	v_cvt_pk_bf16_f32 v10, v12, v13
	v_add_co_u32_e32 v12, vcc, s69, v144
	s_nop 0
	v_lshl_add_u64 v[16:17], v[144:145], 0, s[36:37]
	v_addc_co_u32_e32 v13, vcc, 0, v145, vcc
	s_and_b64 vcc, exec, s[6:7]
	s_mov_b64 s[6:7], -1
	v_cvt_pk_bf16_f32 v11, v14, v15
	global_store_dwordx4 v[12:13], v[8:11], off sc1
	v_cvt_pk_bf16_f32 v4, v4, v5
	v_cvt_pk_bf16_f32 v5, v6, v7
	v_cvt_pk_bf16_f32 v6, v0, v1
	v_cvt_pk_bf16_f32 v7, v2, v3
	global_store_dwordx4 v[16:17], v[4:7], off offset:256 sc1
	s_cbranch_vccnz .LBB0_1502
	s_andn2_b64 vcc, exec, s[0:1]
	s_cbranch_vccnz .LBB0_1501
	s_barrier
	s_branch .LBB0_1501
